# first barrier: census counters requested before the store drain (retry loop kept as fallback)
# speedup vs baseline: 1.0024x; 1.0024x over previous
; __device__ __forceinline__ unsigned xb_ld(unsigned* p)              { return __hip_atomic_load(p, __ATOMIC_RELAXED, __HIP_MEMORY_SCOPE_AGENT); }
; __device__ __forceinline__ void xcd_barrier_complete(unsigned* bar, unsigned x, unsigned& nloc, unsigned& nx) {
;     ...
;         sum = 0u; cnt = 0u; mine = 0u;
; #pragma unroll
;         for (unsigned j = 0; j < 16; ++j) { const unsigned c = xb_ld(&bar[XB_XCNT(j)]); sum += c; cnt += (c > 0u) ? 1u : 0u; mine = (j == x) ? c : mine; }
; __device__ __forceinline__ void xcd_barrier(const XcdBarrier& b) {
;     asm volatile("s_waitcnt vmcnt(0)" ::: "memory");
;     __syncthreads();
;     if (threadIdx.x == 0) {
;         unsigned* bar = b.bar;
;         __builtin_amdgcn_s_waitcnt(0);
;         unsigned nloc = b.st[0], nx = b.st[1];
;         if (nloc == 0u) { xcd_barrier_complete(bar, b.x, nloc, nx); b.st[0] = nloc; b.st[1] = nx; }
.LBB0_123:
	s_cbranch_execz .LBB0_177
	s_and_saveexec_b64 s[96:97], s[0:1]
	v_mov_b32_e32 v216, 0
	global_load_dword v200, v216, s[54:55] offset:1024 sc1
	global_load_dword v201, v216, s[54:55] offset:1280 sc1
	global_load_dword v202, v216, s[54:55] offset:1536 sc1
	global_load_dword v203, v216, s[54:55] offset:1792 sc1
	global_load_dword v204, v216, s[54:55] offset:2048 sc1
	global_load_dword v205, v216, s[54:55] offset:2304 sc1
	global_load_dword v206, v216, s[54:55] offset:2560 sc1
	global_load_dword v207, v216, s[54:55] offset:2816 sc1
	global_load_dword v208, v216, s[54:55] offset:3072 sc1
	global_load_dword v209, v216, s[54:55] offset:3328 sc1
	global_load_dword v210, v216, s[54:55] offset:3584 sc1
	global_load_dword v211, v216, s[54:55] offset:3840 sc1
	s_add_u32 s98, s54, 0x1000
	s_addc_u32 s99, s55, 0
	global_load_dword v212, v216, s[98:99] offset:0 sc1
	global_load_dword v213, v216, s[98:99] offset:256 sc1
	global_load_dword v214, v216, s[98:99] offset:512 sc1
	global_load_dword v215, v216, s[98:99] offset:768 sc1
	s_mov_b64 exec, s[96:97]
	s_waitcnt vmcnt(0)
	s_barrier
	s_and_saveexec_b64 s[2:3], s[0:1]
	s_cbranch_execz .LBB0_176
	s_add_i32 s4, 0, 0x20000
	v_mov_b32_e32 v0, s4
	s_waitcnt vmcnt(0) expcnt(0) lgkmcnt(0)
	ds_read_b32 v2, v0
	s_add_i32 s4, 0, 0x20004
	v_mov_b32_e32 v0, s4
	ds_read_b32 v0, v0
	s_waitcnt lgkmcnt(1)
	v_cmp_ne_u32_e32 vcc, 0, v2
	s_cbranch_vccnz .LBB0_140
	s_add_u32 s4, s54, 0x1000
	s_addc_u32 s5, s55, 0
	s_add_u32 s6, s54, 0x1100
	s_addc_u32 s7, s55, 0
	s_add_u32 s8, s54, 0x1200
	s_addc_u32 s9, s55, 0
	s_mul_i32 s28, s65, s61
	s_add_u32 s20, s54, 0x1300
	s_mul_i32 s28, s28, s64
	s_addc_u32 s21, s55, 0
	s_mov_b32 s29, 1
	v_mov_b32_e32 v16, 0
	s_waitcnt lgkmcnt(0)
	v_mov_b32_e32 v15, v200
	v_mov_b32_e32 v0, v201
	v_mov_b32_e32 v1, v202
	v_mov_b32_e32 v2, v203
	v_mov_b32_e32 v3, v204
	v_mov_b32_e32 v4, v205
	v_mov_b32_e32 v5, v206
	v_mov_b32_e32 v6, v207
	v_mov_b32_e32 v7, v208
	v_mov_b32_e32 v8, v209
	v_mov_b32_e32 v9, v210
	v_mov_b32_e32 v10, v211
	v_mov_b32_e32 v11, v212
	v_mov_b32_e32 v12, v213
	v_mov_b32_e32 v13, v214
	v_mov_b32_e32 v14, v215
	s_branch .Lcensus_have

; __device__ __forceinline__ unsigned xb_ld(unsigned* p)              { return __hip_atomic_load(p, __ATOMIC_RELAXED, __HIP_MEMORY_SCOPE_AGENT); }
; __device__ __forceinline__ void xcd_barrier_complete(unsigned* bar, unsigned x, unsigned& nloc, unsigned& nx) {
;     ...
;     for (;;) {
;         sum = 0u; cnt = 0u; mine = 0u;
; #pragma unroll
;         for (unsigned j = 0; j < 16; ++j) { const unsigned c = xb_ld(&bar[XB_XCNT(j)]); sum += c; cnt += (c > 0u) ? 1u : 0u; mine = (j == x) ? c : mine; }
;         if (sum == G) break;
;         __builtin_amdgcn_s_sleep(1);
;         if ((++sp & 255u) == 0u) { if (xb_ld(&bar[XB_TMO])) break; if (sp > XB_SPIN_CAP) { atomicAdd(&bar[XB_TMO], 1u); break; } }
.Lcensus_have:
	s_mov_b64 s[22:23], -1
	s_mov_b64 s[24:25], -1
	s_waitcnt vmcnt(14)
	v_add_u32_e32 v17, v0, v15
	s_waitcnt vmcnt(13)
	v_add_u32_e32 v17, v17, v1
	s_waitcnt vmcnt(12)
	v_add_u32_e32 v17, v17, v2
	s_waitcnt vmcnt(11)
	v_add_u32_e32 v17, v17, v3
	s_waitcnt vmcnt(10)
	v_add_u32_e32 v17, v17, v4
	s_waitcnt vmcnt(9)
	v_add_u32_e32 v17, v17, v5
	s_waitcnt vmcnt(8)
	v_add_u32_e32 v17, v17, v6
	s_waitcnt vmcnt(7)
	v_add_u32_e32 v17, v17, v7
	s_waitcnt vmcnt(6)
	v_add_u32_e32 v17, v17, v8
	s_waitcnt vmcnt(5)
	v_add_u32_e32 v17, v17, v9
	s_waitcnt vmcnt(4)
	v_add_u32_e32 v17, v17, v10
	s_waitcnt vmcnt(3)
	v_add_u32_e32 v17, v17, v11
	s_waitcnt vmcnt(2)
	v_add_u32_e32 v17, v17, v12
	s_waitcnt vmcnt(1)
	v_add_u32_e32 v17, v17, v13
	s_waitcnt vmcnt(0)
	v_add_u32_e32 v17, v17, v14
	v_cmp_eq_u32_e32 vcc, s28, v17
	s_cbranch_vccnz .LBB0_127
	s_and_b32 s22, s29, 0xff
	s_cmp_eq_u32 s22, 0
	s_mov_b64 s[22:23], -1
	s_mov_b64 s[26:27], -1
	s_sleep 1
	s_cbranch_scc0 .LBB0_132
	global_load_dword v17, v16, s[54:55] offset:512 sc1
	s_waitcnt vmcnt(0)
	v_cmp_eq_u32_e32 vcc, 0, v17
	s_cbranch_vccnz .LBB0_134
	s_mov_b64 s[26:27], 0
